# lever 10 (f32 matrix cores for f32 VALU multiply-accumulate): compression MLP stage 2 product on v_mfma_f32_4x4x1_16b_f32 (f32 operands, exact k-ordered f32 fma chain) instead of packed VALU fmas
# speedup vs baseline: 1.0097x; 1.0020x over previous
.LBB0_1169:
	s_andn2_saveexec_b64 s[12:13], s[12:13]
	v_mul_f32_e32 v36, v35, v35
	v_mov_b32_e32 v37, 0x3ca908c9
	v_fmac_f32_e32 v37, 0xbbbac73d, v36
	v_fmaak_f32 v37, v36, v37, 0xbd5c1c4e
	v_fmaak_f32 v37, v36, v37, 0x3e088382
	v_fmaak_f32 v37, v36, v37, 0xbeaaaa99
	v_mul_f32_e64 v37, |v35|, v37
	v_fma_f32 v36, v36, v37, |v35|
	s_or_b64 exec, exec, s[12:13]
	s_brev_b32 s4, -2
	v_bfi_b32 v35, s4, v36, v35
	v_mul_f32_e32 v34, 0.5, v34
	v_add_f32_e32 v35, 1.0, v35
	v_mul_f32_e32 v34, v34, v35
	v_lshlrev_b32_e32 v36, 5, v1
	ds_write_b32 v39, v34 offset:3840
	v_lshlrev_b32_e32 v34, 4, v1
	v_and_b32_e32 v36, 0xffffc000, v36
	v_and_b32_e32 v35, 0xf0, v34
	v_add_u32_e32 v36, 0, v36
	v_and_b32_e32 v34, 0x1f00, v34
	v_add3_u32 v34, v36, v34, v35
	ds_write_b128 v34, v[2:5] offset:8192
	ds_write_b128 v34, v[6:9] offset:24576
	ds_write_b128 v34, v[10:13] offset:40960
	ds_write_b128 v34, v[14:17] offset:57344
	v_add_u32_e32 v2, 0x12000, v34
	ds_write_b128 v2, v[18:21]
	v_add_u32_e32 v2, 0x16000, v34
	ds_write_b128 v2, v[22:25]
	v_add_u32_e32 v2, 0x1a000, v34
	ds_write_b128 v2, v[26:29]
	v_add_u32_e32 v2, 0x1e000, v34
	ds_write_b128 v2, v[30:33]
	s_waitcnt lgkmcnt(0)
	s_barrier
	v_lshlrev_b32_e32 v40, 2, v106
	v_add_u32_e32 v2, 0, v40
	v_mov_b32_e32 v4, 0
	s_and_b32 s16, s23, 0xffc
	s_mov_b32 s12, 0
	v_add_u32_e32 v39, 0x2000, v2
	v_mov_b32_e32 v5, v4
	v_mov_b32_e32 v2, v4
	v_mov_b32_e32 v3, v4
	v_and_b32_e32 v78, 3, v106
	v_lshlrev_b32_e32 v78, 10, v78
	v_add_u32_e32 v78, s11, v78
	v_mov_b32_e32 v79, v39
	v_mov_b32_e32 v74, 0
	v_mov_b32_e32 v75, 0
	v_mov_b32_e32 v76, 0
	v_mov_b32_e32 v77, 0
	ds_read_b128 v[6:9], v78
	ds_read_b128 v[10:13], v78 offset:16
	ds_read_b128 v[14:17], v78 offset:32
	ds_read_b128 v[18:21], v78 offset:48
	ds_read_b128 v[22:25], v78 offset:64
	ds_read_b128 v[26:29], v78 offset:80
	ds_read_b128 v[30:33], v78 offset:96
	ds_read_b128 v[34:37], v78 offset:112
	ds_read2st64_b32 v[42:43], v79 offset1:1
	ds_read2st64_b32 v[44:45], v79 offset0:2 offset1:3
	ds_read2st64_b32 v[46:47], v79 offset0:4 offset1:5
	ds_read2st64_b32 v[48:49], v79 offset0:6 offset1:7
	ds_read2st64_b32 v[50:51], v79 offset0:8 offset1:9
	ds_read2st64_b32 v[52:53], v79 offset0:10 offset1:11
	ds_read2st64_b32 v[54:55], v79 offset0:12 offset1:13
	ds_read2st64_b32 v[56:57], v79 offset0:14 offset1:15
	ds_read2st64_b32 v[58:59], v79 offset0:16 offset1:17
	ds_read2st64_b32 v[60:61], v79 offset0:18 offset1:19
	ds_read2st64_b32 v[62:63], v79 offset0:20 offset1:21
	ds_read2st64_b32 v[64:65], v79 offset0:22 offset1:23
	ds_read2st64_b32 v[66:67], v79 offset0:24 offset1:25
	ds_read2st64_b32 v[68:69], v79 offset0:26 offset1:27
	ds_read2st64_b32 v[70:71], v79 offset0:28 offset1:29
	ds_read2st64_b32 v[72:73], v79 offset0:30 offset1:31
	s_waitcnt lgkmcnt(0)
	v_add_u32_e32 v79, 0x4000, v79
	ds_read_b128 v[110:113], v78 offset:128
	ds_read_b128 v[114:117], v78 offset:144
	ds_read_b128 v[118:121], v78 offset:160
	ds_read_b128 v[122:125], v78 offset:176
	ds_read_b128 v[126:129], v78 offset:192
	ds_read_b128 v[130:133], v78 offset:208
	ds_read_b128 v[134:137], v78 offset:224
	ds_read_b128 v[138:141], v78 offset:240
	ds_read2st64_b32 v[142:143], v79 offset1:1
	ds_read2st64_b32 v[144:145], v79 offset0:2 offset1:3
	ds_read2st64_b32 v[146:147], v79 offset0:4 offset1:5
	ds_read2st64_b32 v[148:149], v79 offset0:6 offset1:7
	ds_read2st64_b32 v[150:151], v79 offset0:8 offset1:9
	ds_read2st64_b32 v[152:153], v79 offset0:10 offset1:11
	ds_read2st64_b32 v[154:155], v79 offset0:12 offset1:13
	ds_read2st64_b32 v[156:157], v79 offset0:14 offset1:15
	ds_read2st64_b32 v[158:159], v79 offset0:16 offset1:17
	ds_read2st64_b32 v[160:161], v79 offset0:18 offset1:19
	ds_read2st64_b32 v[162:163], v79 offset0:20 offset1:21
	ds_read2st64_b32 v[164:165], v79 offset0:22 offset1:23
	ds_read2st64_b32 v[166:167], v79 offset0:24 offset1:25
	ds_read2st64_b32 v[168:169], v79 offset0:26 offset1:27
	ds_read2st64_b32 v[170:171], v79 offset0:28 offset1:29
	ds_read2st64_b32 v[172:173], v79 offset0:30 offset1:31
	v_mfma_f32_4x4x1_16b_f32 v[74:77], v6, v42, v[74:77]
	s_nop 1
	v_mfma_f32_4x4x1_16b_f32 v[74:77], v7, v43, v[74:77]
	s_nop 1
	v_mfma_f32_4x4x1_16b_f32 v[74:77], v8, v44, v[74:77]
	s_nop 1
	v_mfma_f32_4x4x1_16b_f32 v[74:77], v9, v45, v[74:77]
	s_nop 1
	v_mfma_f32_4x4x1_16b_f32 v[74:77], v10, v46, v[74:77]
	s_nop 1
	v_mfma_f32_4x4x1_16b_f32 v[74:77], v11, v47, v[74:77]
	s_nop 1
	v_mfma_f32_4x4x1_16b_f32 v[74:77], v12, v48, v[74:77]
	s_nop 1
	v_mfma_f32_4x4x1_16b_f32 v[74:77], v13, v49, v[74:77]
	s_nop 1
	v_mfma_f32_4x4x1_16b_f32 v[74:77], v14, v50, v[74:77]
	s_nop 1
	v_mfma_f32_4x4x1_16b_f32 v[74:77], v15, v51, v[74:77]
	s_nop 1
	v_mfma_f32_4x4x1_16b_f32 v[74:77], v16, v52, v[74:77]
	s_nop 1
	v_mfma_f32_4x4x1_16b_f32 v[74:77], v17, v53, v[74:77]
	s_nop 1
	v_mfma_f32_4x4x1_16b_f32 v[74:77], v18, v54, v[74:77]
	s_nop 1
	v_mfma_f32_4x4x1_16b_f32 v[74:77], v19, v55, v[74:77]
	s_nop 1
	v_mfma_f32_4x4x1_16b_f32 v[74:77], v20, v56, v[74:77]
	s_nop 1
	v_mfma_f32_4x4x1_16b_f32 v[74:77], v21, v57, v[74:77]
	s_nop 1
	v_mfma_f32_4x4x1_16b_f32 v[74:77], v22, v58, v[74:77]
	s_nop 1
	v_mfma_f32_4x4x1_16b_f32 v[74:77], v23, v59, v[74:77]
	s_nop 1
	v_mfma_f32_4x4x1_16b_f32 v[74:77], v24, v60, v[74:77]
	s_nop 1
	v_mfma_f32_4x4x1_16b_f32 v[74:77], v25, v61, v[74:77]
	s_nop 1
	v_mfma_f32_4x4x1_16b_f32 v[74:77], v26, v62, v[74:77]
	s_nop 1
	v_mfma_f32_4x4x1_16b_f32 v[74:77], v27, v63, v[74:77]
	s_nop 1
	v_mfma_f32_4x4x1_16b_f32 v[74:77], v28, v64, v[74:77]
	s_nop 1
	v_mfma_f32_4x4x1_16b_f32 v[74:77], v29, v65, v[74:77]
	s_nop 1
	v_mfma_f32_4x4x1_16b_f32 v[74:77], v30, v66, v[74:77]
	s_nop 1
	v_mfma_f32_4x4x1_16b_f32 v[74:77], v31, v67, v[74:77]
	s_nop 1
	v_mfma_f32_4x4x1_16b_f32 v[74:77], v32, v68, v[74:77]
	s_nop 1
	v_mfma_f32_4x4x1_16b_f32 v[74:77], v33, v69, v[74:77]
	s_nop 1
	v_mfma_f32_4x4x1_16b_f32 v[74:77], v34, v70, v[74:77]
	s_nop 1
	v_mfma_f32_4x4x1_16b_f32 v[74:77], v35, v71, v[74:77]
	s_nop 1
	v_mfma_f32_4x4x1_16b_f32 v[74:77], v36, v72, v[74:77]
	s_nop 1
	v_mfma_f32_4x4x1_16b_f32 v[74:77], v37, v73, v[74:77]
	s_nop 1
	s_waitcnt lgkmcnt(0)
	v_add_u32_e32 v79, 0x4000, v79
	ds_read_b128 v[6:9], v78 offset:256
	ds_read_b128 v[10:13], v78 offset:272
	ds_read_b128 v[14:17], v78 offset:288
	ds_read_b128 v[18:21], v78 offset:304
	ds_read_b128 v[22:25], v78 offset:320
	ds_read_b128 v[26:29], v78 offset:336
	ds_read_b128 v[30:33], v78 offset:352
	ds_read_b128 v[34:37], v78 offset:368
	ds_read2st64_b32 v[42:43], v79 offset1:1
	ds_read2st64_b32 v[44:45], v79 offset0:2 offset1:3
	ds_read2st64_b32 v[46:47], v79 offset0:4 offset1:5
	ds_read2st64_b32 v[48:49], v79 offset0:6 offset1:7
	ds_read2st64_b32 v[50:51], v79 offset0:8 offset1:9
	ds_read2st64_b32 v[52:53], v79 offset0:10 offset1:11
	ds_read2st64_b32 v[54:55], v79 offset0:12 offset1:13
	ds_read2st64_b32 v[56:57], v79 offset0:14 offset1:15
	ds_read2st64_b32 v[58:59], v79 offset0:16 offset1:17
	ds_read2st64_b32 v[60:61], v79 offset0:18 offset1:19
	ds_read2st64_b32 v[62:63], v79 offset0:20 offset1:21
	ds_read2st64_b32 v[64:65], v79 offset0:22 offset1:23
	ds_read2st64_b32 v[66:67], v79 offset0:24 offset1:25
	ds_read2st64_b32 v[68:69], v79 offset0:26 offset1:27
	ds_read2st64_b32 v[70:71], v79 offset0:28 offset1:29
	ds_read2st64_b32 v[72:73], v79 offset0:30 offset1:31
	v_mfma_f32_4x4x1_16b_f32 v[74:77], v110, v142, v[74:77]
	s_nop 1
	v_mfma_f32_4x4x1_16b_f32 v[74:77], v111, v143, v[74:77]
	s_nop 1
	v_mfma_f32_4x4x1_16b_f32 v[74:77], v112, v144, v[74:77]
	s_nop 1
	v_mfma_f32_4x4x1_16b_f32 v[74:77], v113, v145, v[74:77]
	s_nop 1
	v_mfma_f32_4x4x1_16b_f32 v[74:77], v114, v146, v[74:77]
	s_nop 1
	v_mfma_f32_4x4x1_16b_f32 v[74:77], v115, v147, v[74:77]
	s_nop 1
	v_mfma_f32_4x4x1_16b_f32 v[74:77], v116, v148, v[74:77]
	s_nop 1
	v_mfma_f32_4x4x1_16b_f32 v[74:77], v117, v149, v[74:77]
	s_nop 1
	v_mfma_f32_4x4x1_16b_f32 v[74:77], v118, v150, v[74:77]
	s_nop 1
	v_mfma_f32_4x4x1_16b_f32 v[74:77], v119, v151, v[74:77]
	s_nop 1
	v_mfma_f32_4x4x1_16b_f32 v[74:77], v120, v152, v[74:77]
	s_nop 1
	v_mfma_f32_4x4x1_16b_f32 v[74:77], v121, v153, v[74:77]
	s_nop 1
	v_mfma_f32_4x4x1_16b_f32 v[74:77], v122, v154, v[74:77]
	s_nop 1
	v_mfma_f32_4x4x1_16b_f32 v[74:77], v123, v155, v[74:77]
	s_nop 1
	v_mfma_f32_4x4x1_16b_f32 v[74:77], v124, v156, v[74:77]
	s_nop 1
	v_mfma_f32_4x4x1_16b_f32 v[74:77], v125, v157, v[74:77]
	s_nop 1
	v_mfma_f32_4x4x1_16b_f32 v[74:77], v126, v158, v[74:77]
	s_nop 1
	v_mfma_f32_4x4x1_16b_f32 v[74:77], v127, v159, v[74:77]
	s_nop 1
	v_mfma_f32_4x4x1_16b_f32 v[74:77], v128, v160, v[74:77]
	s_nop 1
	v_mfma_f32_4x4x1_16b_f32 v[74:77], v129, v161, v[74:77]
	s_nop 1
	v_mfma_f32_4x4x1_16b_f32 v[74:77], v130, v162, v[74:77]
	s_nop 1
	v_mfma_f32_4x4x1_16b_f32 v[74:77], v131, v163, v[74:77]
	s_nop 1
	v_mfma_f32_4x4x1_16b_f32 v[74:77], v132, v164, v[74:77]
	s_nop 1
	v_mfma_f32_4x4x1_16b_f32 v[74:77], v133, v165, v[74:77]
	s_nop 1
	v_mfma_f32_4x4x1_16b_f32 v[74:77], v134, v166, v[74:77]
	s_nop 1
	v_mfma_f32_4x4x1_16b_f32 v[74:77], v135, v167, v[74:77]
	s_nop 1
	v_mfma_f32_4x4x1_16b_f32 v[74:77], v136, v168, v[74:77]
	s_nop 1
	v_mfma_f32_4x4x1_16b_f32 v[74:77], v137, v169, v[74:77]
	s_nop 1
	v_mfma_f32_4x4x1_16b_f32 v[74:77], v138, v170, v[74:77]
	s_nop 1
	v_mfma_f32_4x4x1_16b_f32 v[74:77], v139, v171, v[74:77]
	s_nop 1
	v_mfma_f32_4x4x1_16b_f32 v[74:77], v140, v172, v[74:77]
	s_nop 1
	v_mfma_f32_4x4x1_16b_f32 v[74:77], v141, v173, v[74:77]
	s_nop 1
	s_waitcnt lgkmcnt(0)
	v_add_u32_e32 v79, 0x4000, v79
	ds_read_b128 v[110:113], v78 offset:384
	ds_read_b128 v[114:117], v78 offset:400
	ds_read_b128 v[118:121], v78 offset:416
	ds_read_b128 v[122:125], v78 offset:432
	ds_read_b128 v[126:129], v78 offset:448
	ds_read_b128 v[130:133], v78 offset:464
	ds_read_b128 v[134:137], v78 offset:480
	ds_read_b128 v[138:141], v78 offset:496
	ds_read2st64_b32 v[142:143], v79 offset1:1
	ds_read2st64_b32 v[144:145], v79 offset0:2 offset1:3
	ds_read2st64_b32 v[146:147], v79 offset0:4 offset1:5
	ds_read2st64_b32 v[148:149], v79 offset0:6 offset1:7
	ds_read2st64_b32 v[150:151], v79 offset0:8 offset1:9
	ds_read2st64_b32 v[152:153], v79 offset0:10 offset1:11
	ds_read2st64_b32 v[154:155], v79 offset0:12 offset1:13
	ds_read2st64_b32 v[156:157], v79 offset0:14 offset1:15
	ds_read2st64_b32 v[158:159], v79 offset0:16 offset1:17
	ds_read2st64_b32 v[160:161], v79 offset0:18 offset1:19
	ds_read2st64_b32 v[162:163], v79 offset0:20 offset1:21
	ds_read2st64_b32 v[164:165], v79 offset0:22 offset1:23
	ds_read2st64_b32 v[166:167], v79 offset0:24 offset1:25
	ds_read2st64_b32 v[168:169], v79 offset0:26 offset1:27
	ds_read2st64_b32 v[170:171], v79 offset0:28 offset1:29
	ds_read2st64_b32 v[172:173], v79 offset0:30 offset1:31
	v_mfma_f32_4x4x1_16b_f32 v[74:77], v6, v42, v[74:77]
	s_nop 1
	v_mfma_f32_4x4x1_16b_f32 v[74:77], v7, v43, v[74:77]
	s_nop 1
	v_mfma_f32_4x4x1_16b_f32 v[74:77], v8, v44, v[74:77]
	s_nop 1
	v_mfma_f32_4x4x1_16b_f32 v[74:77], v9, v45, v[74:77]
	s_nop 1
	v_mfma_f32_4x4x1_16b_f32 v[74:77], v10, v46, v[74:77]
	s_nop 1
	v_mfma_f32_4x4x1_16b_f32 v[74:77], v11, v47, v[74:77]
	s_nop 1
	v_mfma_f32_4x4x1_16b_f32 v[74:77], v12, v48, v[74:77]
	s_nop 1
	v_mfma_f32_4x4x1_16b_f32 v[74:77], v13, v49, v[74:77]
	s_nop 1
	v_mfma_f32_4x4x1_16b_f32 v[74:77], v14, v50, v[74:77]
	s_nop 1
	v_mfma_f32_4x4x1_16b_f32 v[74:77], v15, v51, v[74:77]
	s_nop 1
	v_mfma_f32_4x4x1_16b_f32 v[74:77], v16, v52, v[74:77]
	s_nop 1
	v_mfma_f32_4x4x1_16b_f32 v[74:77], v17, v53, v[74:77]
	s_nop 1
	v_mfma_f32_4x4x1_16b_f32 v[74:77], v18, v54, v[74:77]
	s_nop 1
	v_mfma_f32_4x4x1_16b_f32 v[74:77], v19, v55, v[74:77]
	s_nop 1
	v_mfma_f32_4x4x1_16b_f32 v[74:77], v20, v56, v[74:77]
	s_nop 1
	v_mfma_f32_4x4x1_16b_f32 v[74:77], v21, v57, v[74:77]
	s_nop 1
	v_mfma_f32_4x4x1_16b_f32 v[74:77], v22, v58, v[74:77]
	s_nop 1
	v_mfma_f32_4x4x1_16b_f32 v[74:77], v23, v59, v[74:77]
	s_nop 1
	v_mfma_f32_4x4x1_16b_f32 v[74:77], v24, v60, v[74:77]
	s_nop 1
	v_mfma_f32_4x4x1_16b_f32 v[74:77], v25, v61, v[74:77]
	s_nop 1
	v_mfma_f32_4x4x1_16b_f32 v[74:77], v26, v62, v[74:77]
	s_nop 1
	v_mfma_f32_4x4x1_16b_f32 v[74:77], v27, v63, v[74:77]
	s_nop 1
	v_mfma_f32_4x4x1_16b_f32 v[74:77], v28, v64, v[74:77]
	s_nop 1
	v_mfma_f32_4x4x1_16b_f32 v[74:77], v29, v65, v[74:77]
	s_nop 1
	v_mfma_f32_4x4x1_16b_f32 v[74:77], v30, v66, v[74:77]
	s_nop 1
	v_mfma_f32_4x4x1_16b_f32 v[74:77], v31, v67, v[74:77]
	s_nop 1
	v_mfma_f32_4x4x1_16b_f32 v[74:77], v32, v68, v[74:77]
	s_nop 1
	v_mfma_f32_4x4x1_16b_f32 v[74:77], v33, v69, v[74:77]
	s_nop 1
	v_mfma_f32_4x4x1_16b_f32 v[74:77], v34, v70, v[74:77]
	s_nop 1
	v_mfma_f32_4x4x1_16b_f32 v[74:77], v35, v71, v[74:77]
	s_nop 1
	v_mfma_f32_4x4x1_16b_f32 v[74:77], v36, v72, v[74:77]
	s_nop 1
	v_mfma_f32_4x4x1_16b_f32 v[74:77], v37, v73, v[74:77]
	s_nop 1
	s_waitcnt lgkmcnt(0)
	v_add_u32_e32 v79, 0x4000, v79
	ds_read_b128 v[6:9], v78 offset:512
	ds_read_b128 v[10:13], v78 offset:528
	ds_read_b128 v[14:17], v78 offset:544
	ds_read_b128 v[18:21], v78 offset:560
	ds_read_b128 v[22:25], v78 offset:576
	ds_read_b128 v[26:29], v78 offset:592
	ds_read_b128 v[30:33], v78 offset:608
	ds_read_b128 v[34:37], v78 offset:624
	ds_read2st64_b32 v[42:43], v79 offset1:1
	ds_read2st64_b32 v[44:45], v79 offset0:2 offset1:3
	ds_read2st64_b32 v[46:47], v79 offset0:4 offset1:5
	ds_read2st64_b32 v[48:49], v79 offset0:6 offset1:7
	ds_read2st64_b32 v[50:51], v79 offset0:8 offset1:9
	ds_read2st64_b32 v[52:53], v79 offset0:10 offset1:11
	ds_read2st64_b32 v[54:55], v79 offset0:12 offset1:13
	ds_read2st64_b32 v[56:57], v79 offset0:14 offset1:15
	ds_read2st64_b32 v[58:59], v79 offset0:16 offset1:17
	ds_read2st64_b32 v[60:61], v79 offset0:18 offset1:19
	ds_read2st64_b32 v[62:63], v79 offset0:20 offset1:21
	ds_read2st64_b32 v[64:65], v79 offset0:22 offset1:23
	ds_read2st64_b32 v[66:67], v79 offset0:24 offset1:25
	ds_read2st64_b32 v[68:69], v79 offset0:26 offset1:27
	ds_read2st64_b32 v[70:71], v79 offset0:28 offset1:29
	ds_read2st64_b32 v[72:73], v79 offset0:30 offset1:31
	v_mfma_f32_4x4x1_16b_f32 v[74:77], v110, v142, v[74:77]
	s_nop 1
	v_mfma_f32_4x4x1_16b_f32 v[74:77], v111, v143, v[74:77]
	s_nop 1
	v_mfma_f32_4x4x1_16b_f32 v[74:77], v112, v144, v[74:77]
	s_nop 1
	v_mfma_f32_4x4x1_16b_f32 v[74:77], v113, v145, v[74:77]
	s_nop 1
	v_mfma_f32_4x4x1_16b_f32 v[74:77], v114, v146, v[74:77]
	s_nop 1
	v_mfma_f32_4x4x1_16b_f32 v[74:77], v115, v147, v[74:77]
	s_nop 1
	v_mfma_f32_4x4x1_16b_f32 v[74:77], v116, v148, v[74:77]
	s_nop 1
	v_mfma_f32_4x4x1_16b_f32 v[74:77], v117, v149, v[74:77]
	s_nop 1
	v_mfma_f32_4x4x1_16b_f32 v[74:77], v118, v150, v[74:77]
	s_nop 1
	v_mfma_f32_4x4x1_16b_f32 v[74:77], v119, v151, v[74:77]
	s_nop 1
	v_mfma_f32_4x4x1_16b_f32 v[74:77], v120, v152, v[74:77]
	s_nop 1
	v_mfma_f32_4x4x1_16b_f32 v[74:77], v121, v153, v[74:77]
	s_nop 1
	v_mfma_f32_4x4x1_16b_f32 v[74:77], v122, v154, v[74:77]
	s_nop 1
	v_mfma_f32_4x4x1_16b_f32 v[74:77], v123, v155, v[74:77]
	s_nop 1
	v_mfma_f32_4x4x1_16b_f32 v[74:77], v124, v156, v[74:77]
	s_nop 1
	v_mfma_f32_4x4x1_16b_f32 v[74:77], v125, v157, v[74:77]
	s_nop 1
	v_mfma_f32_4x4x1_16b_f32 v[74:77], v126, v158, v[74:77]
	s_nop 1
	v_mfma_f32_4x4x1_16b_f32 v[74:77], v127, v159, v[74:77]
	s_nop 1
	v_mfma_f32_4x4x1_16b_f32 v[74:77], v128, v160, v[74:77]
	s_nop 1
	v_mfma_f32_4x4x1_16b_f32 v[74:77], v129, v161, v[74:77]
	s_nop 1
	v_mfma_f32_4x4x1_16b_f32 v[74:77], v130, v162, v[74:77]
	s_nop 1
	v_mfma_f32_4x4x1_16b_f32 v[74:77], v131, v163, v[74:77]
	s_nop 1
	v_mfma_f32_4x4x1_16b_f32 v[74:77], v132, v164, v[74:77]
	s_nop 1
	v_mfma_f32_4x4x1_16b_f32 v[74:77], v133, v165, v[74:77]
	s_nop 1
	v_mfma_f32_4x4x1_16b_f32 v[74:77], v134, v166, v[74:77]
	s_nop 1
	v_mfma_f32_4x4x1_16b_f32 v[74:77], v135, v167, v[74:77]
	s_nop 1
	v_mfma_f32_4x4x1_16b_f32 v[74:77], v136, v168, v[74:77]
	s_nop 1
	v_mfma_f32_4x4x1_16b_f32 v[74:77], v137, v169, v[74:77]
	s_nop 1
	v_mfma_f32_4x4x1_16b_f32 v[74:77], v138, v170, v[74:77]
	s_nop 1
	v_mfma_f32_4x4x1_16b_f32 v[74:77], v139, v171, v[74:77]
	s_nop 1
	v_mfma_f32_4x4x1_16b_f32 v[74:77], v140, v172, v[74:77]
	s_nop 1
	v_mfma_f32_4x4x1_16b_f32 v[74:77], v141, v173, v[74:77]
	s_nop 1
	s_waitcnt lgkmcnt(0)
	v_add_u32_e32 v79, 0x4000, v79
	ds_read_b128 v[110:113], v78 offset:640
	ds_read_b128 v[114:117], v78 offset:656
	ds_read_b128 v[118:121], v78 offset:672
	ds_read_b128 v[122:125], v78 offset:688
	ds_read_b128 v[126:129], v78 offset:704
	ds_read_b128 v[130:133], v78 offset:720
	ds_read_b128 v[134:137], v78 offset:736
	ds_read_b128 v[138:141], v78 offset:752
	ds_read2st64_b32 v[142:143], v79 offset1:1
	ds_read2st64_b32 v[144:145], v79 offset0:2 offset1:3
	ds_read2st64_b32 v[146:147], v79 offset0:4 offset1:5
	ds_read2st64_b32 v[148:149], v79 offset0:6 offset1:7
	ds_read2st64_b32 v[150:151], v79 offset0:8 offset1:9
	ds_read2st64_b32 v[152:153], v79 offset0:10 offset1:11
	ds_read2st64_b32 v[154:155], v79 offset0:12 offset1:13
	ds_read2st64_b32 v[156:157], v79 offset0:14 offset1:15
	ds_read2st64_b32 v[158:159], v79 offset0:16 offset1:17
	ds_read2st64_b32 v[160:161], v79 offset0:18 offset1:19
	ds_read2st64_b32 v[162:163], v79 offset0:20 offset1:21
	ds_read2st64_b32 v[164:165], v79 offset0:22 offset1:23
	ds_read2st64_b32 v[166:167], v79 offset0:24 offset1:25
	ds_read2st64_b32 v[168:169], v79 offset0:26 offset1:27
	ds_read2st64_b32 v[170:171], v79 offset0:28 offset1:29
	ds_read2st64_b32 v[172:173], v79 offset0:30 offset1:31
	v_mfma_f32_4x4x1_16b_f32 v[74:77], v6, v42, v[74:77]
	s_nop 1
	v_mfma_f32_4x4x1_16b_f32 v[74:77], v7, v43, v[74:77]
	s_nop 1
	v_mfma_f32_4x4x1_16b_f32 v[74:77], v8, v44, v[74:77]
	s_nop 1
	v_mfma_f32_4x4x1_16b_f32 v[74:77], v9, v45, v[74:77]
	s_nop 1
	v_mfma_f32_4x4x1_16b_f32 v[74:77], v10, v46, v[74:77]
	s_nop 1
	v_mfma_f32_4x4x1_16b_f32 v[74:77], v11, v47, v[74:77]
	s_nop 1
	v_mfma_f32_4x4x1_16b_f32 v[74:77], v12, v48, v[74:77]
	s_nop 1
	v_mfma_f32_4x4x1_16b_f32 v[74:77], v13, v49, v[74:77]
	s_nop 1
	v_mfma_f32_4x4x1_16b_f32 v[74:77], v14, v50, v[74:77]
	s_nop 1
	v_mfma_f32_4x4x1_16b_f32 v[74:77], v15, v51, v[74:77]
	s_nop 1
	v_mfma_f32_4x4x1_16b_f32 v[74:77], v16, v52, v[74:77]
	s_nop 1
	v_mfma_f32_4x4x1_16b_f32 v[74:77], v17, v53, v[74:77]
	s_nop 1
	v_mfma_f32_4x4x1_16b_f32 v[74:77], v18, v54, v[74:77]
	s_nop 1
	v_mfma_f32_4x4x1_16b_f32 v[74:77], v19, v55, v[74:77]
	s_nop 1
	v_mfma_f32_4x4x1_16b_f32 v[74:77], v20, v56, v[74:77]
	s_nop 1
	v_mfma_f32_4x4x1_16b_f32 v[74:77], v21, v57, v[74:77]
	s_nop 1
	v_mfma_f32_4x4x1_16b_f32 v[74:77], v22, v58, v[74:77]
	s_nop 1
	v_mfma_f32_4x4x1_16b_f32 v[74:77], v23, v59, v[74:77]
	s_nop 1
	v_mfma_f32_4x4x1_16b_f32 v[74:77], v24, v60, v[74:77]
	s_nop 1
	v_mfma_f32_4x4x1_16b_f32 v[74:77], v25, v61, v[74:77]
	s_nop 1
	v_mfma_f32_4x4x1_16b_f32 v[74:77], v26, v62, v[74:77]
	s_nop 1
	v_mfma_f32_4x4x1_16b_f32 v[74:77], v27, v63, v[74:77]
	s_nop 1
	v_mfma_f32_4x4x1_16b_f32 v[74:77], v28, v64, v[74:77]
	s_nop 1
	v_mfma_f32_4x4x1_16b_f32 v[74:77], v29, v65, v[74:77]
	s_nop 1
	v_mfma_f32_4x4x1_16b_f32 v[74:77], v30, v66, v[74:77]
	s_nop 1
	v_mfma_f32_4x4x1_16b_f32 v[74:77], v31, v67, v[74:77]
	s_nop 1
	v_mfma_f32_4x4x1_16b_f32 v[74:77], v32, v68, v[74:77]
	s_nop 1
	v_mfma_f32_4x4x1_16b_f32 v[74:77], v33, v69, v[74:77]
	s_nop 1
	v_mfma_f32_4x4x1_16b_f32 v[74:77], v34, v70, v[74:77]
	s_nop 1
	v_mfma_f32_4x4x1_16b_f32 v[74:77], v35, v71, v[74:77]
	s_nop 1
	v_mfma_f32_4x4x1_16b_f32 v[74:77], v36, v72, v[74:77]
	s_nop 1
	v_mfma_f32_4x4x1_16b_f32 v[74:77], v37, v73, v[74:77]
	s_nop 1
	s_waitcnt lgkmcnt(0)
	v_add_u32_e32 v79, 0x4000, v79
	ds_read_b128 v[6:9], v78 offset:768
	ds_read_b128 v[10:13], v78 offset:784
	ds_read_b128 v[14:17], v78 offset:800
	ds_read_b128 v[18:21], v78 offset:816
	ds_read_b128 v[22:25], v78 offset:832
	ds_read_b128 v[26:29], v78 offset:848
	ds_read_b128 v[30:33], v78 offset:864
	ds_read_b128 v[34:37], v78 offset:880
	ds_read2st64_b32 v[42:43], v79 offset1:1
	ds_read2st64_b32 v[44:45], v79 offset0:2 offset1:3
	ds_read2st64_b32 v[46:47], v79 offset0:4 offset1:5
	ds_read2st64_b32 v[48:49], v79 offset0:6 offset1:7
	ds_read2st64_b32 v[50:51], v79 offset0:8 offset1:9
	ds_read2st64_b32 v[52:53], v79 offset0:10 offset1:11
	ds_read2st64_b32 v[54:55], v79 offset0:12 offset1:13
	ds_read2st64_b32 v[56:57], v79 offset0:14 offset1:15
	ds_read2st64_b32 v[58:59], v79 offset0:16 offset1:17
	ds_read2st64_b32 v[60:61], v79 offset0:18 offset1:19
	ds_read2st64_b32 v[62:63], v79 offset0:20 offset1:21
	ds_read2st64_b32 v[64:65], v79 offset0:22 offset1:23
	ds_read2st64_b32 v[66:67], v79 offset0:24 offset1:25
	ds_read2st64_b32 v[68:69], v79 offset0:26 offset1:27
	ds_read2st64_b32 v[70:71], v79 offset0:28 offset1:29
	ds_read2st64_b32 v[72:73], v79 offset0:30 offset1:31
	v_mfma_f32_4x4x1_16b_f32 v[74:77], v110, v142, v[74:77]
	s_nop 1
	v_mfma_f32_4x4x1_16b_f32 v[74:77], v111, v143, v[74:77]
	s_nop 1
	v_mfma_f32_4x4x1_16b_f32 v[74:77], v112, v144, v[74:77]
	s_nop 1
	v_mfma_f32_4x4x1_16b_f32 v[74:77], v113, v145, v[74:77]
	s_nop 1
	v_mfma_f32_4x4x1_16b_f32 v[74:77], v114, v146, v[74:77]
	s_nop 1
	v_mfma_f32_4x4x1_16b_f32 v[74:77], v115, v147, v[74:77]
	s_nop 1
	v_mfma_f32_4x4x1_16b_f32 v[74:77], v116, v148, v[74:77]
	s_nop 1
	v_mfma_f32_4x4x1_16b_f32 v[74:77], v117, v149, v[74:77]
	s_nop 1
	v_mfma_f32_4x4x1_16b_f32 v[74:77], v118, v150, v[74:77]
	s_nop 1
	v_mfma_f32_4x4x1_16b_f32 v[74:77], v119, v151, v[74:77]
	s_nop 1
	v_mfma_f32_4x4x1_16b_f32 v[74:77], v120, v152, v[74:77]
	s_nop 1
	v_mfma_f32_4x4x1_16b_f32 v[74:77], v121, v153, v[74:77]
	s_nop 1
	v_mfma_f32_4x4x1_16b_f32 v[74:77], v122, v154, v[74:77]
	s_nop 1
	v_mfma_f32_4x4x1_16b_f32 v[74:77], v123, v155, v[74:77]
	s_nop 1
	v_mfma_f32_4x4x1_16b_f32 v[74:77], v124, v156, v[74:77]
	s_nop 1
	v_mfma_f32_4x4x1_16b_f32 v[74:77], v125, v157, v[74:77]
	s_nop 1
	v_mfma_f32_4x4x1_16b_f32 v[74:77], v126, v158, v[74:77]
	s_nop 1
	v_mfma_f32_4x4x1_16b_f32 v[74:77], v127, v159, v[74:77]
	s_nop 1
	v_mfma_f32_4x4x1_16b_f32 v[74:77], v128, v160, v[74:77]
	s_nop 1
	v_mfma_f32_4x4x1_16b_f32 v[74:77], v129, v161, v[74:77]
	s_nop 1
	v_mfma_f32_4x4x1_16b_f32 v[74:77], v130, v162, v[74:77]
	s_nop 1
	v_mfma_f32_4x4x1_16b_f32 v[74:77], v131, v163, v[74:77]
	s_nop 1
	v_mfma_f32_4x4x1_16b_f32 v[74:77], v132, v164, v[74:77]
	s_nop 1
	v_mfma_f32_4x4x1_16b_f32 v[74:77], v133, v165, v[74:77]
	s_nop 1
	v_mfma_f32_4x4x1_16b_f32 v[74:77], v134, v166, v[74:77]
	s_nop 1
	v_mfma_f32_4x4x1_16b_f32 v[74:77], v135, v167, v[74:77]
	s_nop 1
	v_mfma_f32_4x4x1_16b_f32 v[74:77], v136, v168, v[74:77]
	s_nop 1
	v_mfma_f32_4x4x1_16b_f32 v[74:77], v137, v169, v[74:77]
	s_nop 1
	v_mfma_f32_4x4x1_16b_f32 v[74:77], v138, v170, v[74:77]
	s_nop 1
	v_mfma_f32_4x4x1_16b_f32 v[74:77], v139, v171, v[74:77]
	s_nop 1
	v_mfma_f32_4x4x1_16b_f32 v[74:77], v140, v172, v[74:77]
	s_nop 1
	v_mfma_f32_4x4x1_16b_f32 v[74:77], v141, v173, v[74:77]
	s_nop 1
	s_waitcnt lgkmcnt(0)
	v_add_u32_e32 v79, 0x4000, v79
	ds_read_b128 v[110:113], v78 offset:896
	ds_read_b128 v[114:117], v78 offset:912
	ds_read_b128 v[118:121], v78 offset:928
	ds_read_b128 v[122:125], v78 offset:944
	ds_read_b128 v[126:129], v78 offset:960
	ds_read_b128 v[130:133], v78 offset:976
	ds_read_b128 v[134:137], v78 offset:992
	ds_read_b128 v[138:141], v78 offset:1008
	ds_read2st64_b32 v[142:143], v79 offset1:1
	ds_read2st64_b32 v[144:145], v79 offset0:2 offset1:3
	ds_read2st64_b32 v[146:147], v79 offset0:4 offset1:5
	ds_read2st64_b32 v[148:149], v79 offset0:6 offset1:7
	ds_read2st64_b32 v[150:151], v79 offset0:8 offset1:9
	ds_read2st64_b32 v[152:153], v79 offset0:10 offset1:11
	ds_read2st64_b32 v[154:155], v79 offset0:12 offset1:13
	ds_read2st64_b32 v[156:157], v79 offset0:14 offset1:15
	ds_read2st64_b32 v[158:159], v79 offset0:16 offset1:17
	ds_read2st64_b32 v[160:161], v79 offset0:18 offset1:19
	ds_read2st64_b32 v[162:163], v79 offset0:20 offset1:21
	ds_read2st64_b32 v[164:165], v79 offset0:22 offset1:23
	ds_read2st64_b32 v[166:167], v79 offset0:24 offset1:25
	ds_read2st64_b32 v[168:169], v79 offset0:26 offset1:27
	ds_read2st64_b32 v[170:171], v79 offset0:28 offset1:29
	ds_read2st64_b32 v[172:173], v79 offset0:30 offset1:31
	v_mfma_f32_4x4x1_16b_f32 v[74:77], v6, v42, v[74:77]
	s_nop 1
	v_mfma_f32_4x4x1_16b_f32 v[74:77], v7, v43, v[74:77]
	s_nop 1
	v_mfma_f32_4x4x1_16b_f32 v[74:77], v8, v44, v[74:77]
	s_nop 1
	v_mfma_f32_4x4x1_16b_f32 v[74:77], v9, v45, v[74:77]
	s_nop 1
	v_mfma_f32_4x4x1_16b_f32 v[74:77], v10, v46, v[74:77]
	s_nop 1
	v_mfma_f32_4x4x1_16b_f32 v[74:77], v11, v47, v[74:77]
	s_nop 1
	v_mfma_f32_4x4x1_16b_f32 v[74:77], v12, v48, v[74:77]
	s_nop 1
	v_mfma_f32_4x4x1_16b_f32 v[74:77], v13, v49, v[74:77]
	s_nop 1
	v_mfma_f32_4x4x1_16b_f32 v[74:77], v14, v50, v[74:77]
	s_nop 1
	v_mfma_f32_4x4x1_16b_f32 v[74:77], v15, v51, v[74:77]
	s_nop 1
	v_mfma_f32_4x4x1_16b_f32 v[74:77], v16, v52, v[74:77]
	s_nop 1
	v_mfma_f32_4x4x1_16b_f32 v[74:77], v17, v53, v[74:77]
	s_nop 1
	v_mfma_f32_4x4x1_16b_f32 v[74:77], v18, v54, v[74:77]
	s_nop 1
	v_mfma_f32_4x4x1_16b_f32 v[74:77], v19, v55, v[74:77]
	s_nop 1
	v_mfma_f32_4x4x1_16b_f32 v[74:77], v20, v56, v[74:77]
	s_nop 1
	v_mfma_f32_4x4x1_16b_f32 v[74:77], v21, v57, v[74:77]
	s_nop 1
	v_mfma_f32_4x4x1_16b_f32 v[74:77], v22, v58, v[74:77]
	s_nop 1
	v_mfma_f32_4x4x1_16b_f32 v[74:77], v23, v59, v[74:77]
	s_nop 1
	v_mfma_f32_4x4x1_16b_f32 v[74:77], v24, v60, v[74:77]
	s_nop 1
	v_mfma_f32_4x4x1_16b_f32 v[74:77], v25, v61, v[74:77]
	s_nop 1
	v_mfma_f32_4x4x1_16b_f32 v[74:77], v26, v62, v[74:77]
	s_nop 1
	v_mfma_f32_4x4x1_16b_f32 v[74:77], v27, v63, v[74:77]
	s_nop 1
	v_mfma_f32_4x4x1_16b_f32 v[74:77], v28, v64, v[74:77]
	s_nop 1
	v_mfma_f32_4x4x1_16b_f32 v[74:77], v29, v65, v[74:77]
	s_nop 1
	v_mfma_f32_4x4x1_16b_f32 v[74:77], v30, v66, v[74:77]
	s_nop 1
	v_mfma_f32_4x4x1_16b_f32 v[74:77], v31, v67, v[74:77]
	s_nop 1
	v_mfma_f32_4x4x1_16b_f32 v[74:77], v32, v68, v[74:77]
	s_nop 1
	v_mfma_f32_4x4x1_16b_f32 v[74:77], v33, v69, v[74:77]
	s_nop 1
	v_mfma_f32_4x4x1_16b_f32 v[74:77], v34, v70, v[74:77]
	s_nop 1
	v_mfma_f32_4x4x1_16b_f32 v[74:77], v35, v71, v[74:77]
	s_nop 1
	v_mfma_f32_4x4x1_16b_f32 v[74:77], v36, v72, v[74:77]
	s_nop 1
	v_mfma_f32_4x4x1_16b_f32 v[74:77], v37, v73, v[74:77]
	s_nop 1
	s_waitcnt lgkmcnt(0)
	v_mfma_f32_4x4x1_16b_f32 v[74:77], v110, v142, v[74:77]
	s_nop 1
	v_mfma_f32_4x4x1_16b_f32 v[74:77], v111, v143, v[74:77]
	s_nop 1
	v_mfma_f32_4x4x1_16b_f32 v[74:77], v112, v144, v[74:77]
	s_nop 1
	v_mfma_f32_4x4x1_16b_f32 v[74:77], v113, v145, v[74:77]
	s_nop 1
	v_mfma_f32_4x4x1_16b_f32 v[74:77], v114, v146, v[74:77]
	s_nop 1
	v_mfma_f32_4x4x1_16b_f32 v[74:77], v115, v147, v[74:77]
	s_nop 1
	v_mfma_f32_4x4x1_16b_f32 v[74:77], v116, v148, v[74:77]
	s_nop 1
	v_mfma_f32_4x4x1_16b_f32 v[74:77], v117, v149, v[74:77]
	s_nop 1
	v_mfma_f32_4x4x1_16b_f32 v[74:77], v118, v150, v[74:77]
	s_nop 1
	v_mfma_f32_4x4x1_16b_f32 v[74:77], v119, v151, v[74:77]
	s_nop 1
	v_mfma_f32_4x4x1_16b_f32 v[74:77], v120, v152, v[74:77]
	s_nop 1
	v_mfma_f32_4x4x1_16b_f32 v[74:77], v121, v153, v[74:77]
	s_nop 1
	v_mfma_f32_4x4x1_16b_f32 v[74:77], v122, v154, v[74:77]
	s_nop 1
	v_mfma_f32_4x4x1_16b_f32 v[74:77], v123, v155, v[74:77]
	s_nop 1
	v_mfma_f32_4x4x1_16b_f32 v[74:77], v124, v156, v[74:77]
	s_nop 1
	v_mfma_f32_4x4x1_16b_f32 v[74:77], v125, v157, v[74:77]
	s_nop 1
	v_mfma_f32_4x4x1_16b_f32 v[74:77], v126, v158, v[74:77]
	s_nop 1
	v_mfma_f32_4x4x1_16b_f32 v[74:77], v127, v159, v[74:77]
	s_nop 1
	v_mfma_f32_4x4x1_16b_f32 v[74:77], v128, v160, v[74:77]
	s_nop 1
	v_mfma_f32_4x4x1_16b_f32 v[74:77], v129, v161, v[74:77]
	s_nop 1
	v_mfma_f32_4x4x1_16b_f32 v[74:77], v130, v162, v[74:77]
	s_nop 1
	v_mfma_f32_4x4x1_16b_f32 v[74:77], v131, v163, v[74:77]
	s_nop 1
	v_mfma_f32_4x4x1_16b_f32 v[74:77], v132, v164, v[74:77]
	s_nop 1
	v_mfma_f32_4x4x1_16b_f32 v[74:77], v133, v165, v[74:77]
	s_nop 1
	v_mfma_f32_4x4x1_16b_f32 v[74:77], v134, v166, v[74:77]
	s_nop 1
	v_mfma_f32_4x4x1_16b_f32 v[74:77], v135, v167, v[74:77]
	s_nop 1
	v_mfma_f32_4x4x1_16b_f32 v[74:77], v136, v168, v[74:77]
	s_nop 1
	v_mfma_f32_4x4x1_16b_f32 v[74:77], v137, v169, v[74:77]
	s_nop 1
	v_mfma_f32_4x4x1_16b_f32 v[74:77], v138, v170, v[74:77]
	s_nop 1
	v_mfma_f32_4x4x1_16b_f32 v[74:77], v139, v171, v[74:77]
	s_nop 1
	v_mfma_f32_4x4x1_16b_f32 v[74:77], v140, v172, v[74:77]
	s_nop 1
	v_mfma_f32_4x4x1_16b_f32 v[74:77], v141, v173, v[74:77]
	s_nop 1
	s_nop 4
	v_mov_b32_e32 v4, v74
	v_mov_b32_e32 v5, v75
	v_mov_b32_e32 v2, v76
	v_mov_b32_e32 v3, v77
	s_ashr_i32 s11, s10, 31
	s_lshl_b64 s[4:5], s[10:11], 19
	s_add_u32 s4, s6, s4
	s_addc_u32 s5, s7, s5
	v_mov_b32_e32 v39, 0
	v_lshl_add_u64 v[6:7], s[4:5], 0, v[38:39]
	s_mov_b64 s[4:5], 0x5c00000
	v_lshl_add_u64 v[6:7], v[6:7], 0, s[4:5]
	s_lshr_b32 s4, s22, 1
	s_lshr_b32 s5, s23, 4
	s_and_b32 s17, s4, 4
	s_add_u32 s10, s6, 0x7e80000
	v_and_b32_e32 v8, 31, v1
	s_addc_u32 s11, s7, 0
	v_lshrrev_b32_e32 v9, 3, v1
	s_lshl_b32 s3, s3, 5
	v_and_b32_e32 v1, 7, v1
	v_and_or_b32 v14, s3, 32, v8
	v_lshlrev_b32_e32 v38, 1, v1
	v_bfe_u32 v1, v4, 16, 1
	s_movk_i32 s3, 0x7fff
	s_mov_b32 s13, 0
	v_and_b32_e32 v9, 4, v9
	v_add3_u32 v1, v4, v1, s3
	s_lshl_b32 s12, s16, 7
	s_lshr_b32 s4, s23, 3
	v_and_or_b32 v12, s5, 3, v9
	v_lshrrev_b32_e32 v13, 16, v1
	v_lshl_add_u64 v[8:9], v[6:7], 0, s[12:13]
	s_and_b32 s18, s4, 0x1c0
	v_lshl_add_u64 v[10:11], s[6:7], 0, v[38:39]
	s_mov_b64 s[6:7], 0x7e00000
	global_store_short v[8:9], v13, off
	s_bfe_u32 s19, s23, 0x30006
	s_mov_b64 s[14:15], -1
	s_and_b64 vcc, exec, s[8:9]
	v_lshlrev_b32_e32 v8, 4, v14
	s_cbranch_vccz .LBB0_1175
	s_lshl_b32 s3, s19, 3
	s_or_b32 s3, s3, s18
	v_or_b32_e32 v1, s3, v12
	v_lshlrev_b32_e32 v38, 10, v1
	v_mov_b32_e32 v9, v39
	v_lshl_add_u64 v[14:15], s[10:11], 0, v[38:39]
	v_lshl_add_u64 v[14:15], v[14:15], 0, v[8:9]
	s_lshl_b32 s12, s17, 1
	v_lshl_add_u64 v[14:15], v[14:15], 0, s[12:13]
	global_store_short v[14:15], v13, off
	s_mov_b64 s[14:15], 0
